# grid barrier: drop the per-XCD generation atomic (dead since every block polls the top generation word), so the XCD-last blocks no longer wait for it before leaving the barrier
# baseline (speedup 1.0000x reference)
.LBB0_59:
	s_or_b64 exec, exec, s[38:39]
	s_mov_b64 s[38:39], exec
	v_mbcnt_lo_u32_b32 v0, s38, 0
	v_mbcnt_hi_u32_b32 v0, s39, v0
	v_cmp_eq_u32_e32 vcc, 0, v0
	s_waitcnt vmcnt(0)
	buffer_inv sc1
	s_and_saveexec_b64 s[40:41], vcc
	s_cbranch_execz .LBB0_61
	s_bcnt1_i32_b64 s2, s[38:39]
	v_readlane_b32 s38, v240, 10
	v_mov_b32_e32 v0, s2
	v_readlane_b32 s39, v240, 11
	s_nop 4
	s_nop 0
